# scan producer: 16-lane reductions of (v42,v43) with fused v_add_f32_dpp (21 fewer instructions per chunk and producer wave)
# speedup vs baseline: 1.0093x; 1.0093x over previous
.LBB0_840:
	s_waitcnt lgkmcnt(1)
	v_mul_f32_e32 v46, 0xbfb8aa3b, v46
	v_exp_f32_e32 v122, v46
	s_waitcnt lgkmcnt(0)
	v_add_f32_e32 v46, -1.0, v42
	v_fma_f32 v135, v6, v46, 1.0
	v_mul_f32_e32 v46, 0xbfb8aa3b, v47
	v_lshlrev_b32_e32 v130, 16, v70
	v_and_b32_e32 v131, 0xffff0000, v70
	v_lshlrev_b32_e32 v132, 16, v71
	v_and_b32_e32 v142, 0xffff0000, v71
	v_exp_f32_e32 v123, v46
	v_add_f32_e32 v46, -1.0, v43
	v_add_f32_e32 v133, -1.0, v44
	v_add_f32_e32 v143, -1.0, v45
	v_fma_f32 v47, v7, v46, 1.0
	v_mul_f32_e32 v46, 0xbfb8aa3b, v48
	v_pk_mul_f32 v[136:137], v[78:79], v[142:143]
	v_pk_mul_f32 v[148:149], v[2:3], v[130:131]
	v_pk_mul_f32 v[152:153], v[4:5], v[132:133]
	v_exp_f32_e32 v124, v46
	v_mul_f32_e32 v46, 0xbfb8aa3b, v49
	v_xor_b32_e32 v48, 0x80000000, v43
	v_mov_b32_e32 v43, v130
	v_pk_mul_f32 v[150:151], v[148:149], v[148:149]
	v_mov_b32_e32 v49, v131
	v_mov_b32_e32 v130, v136
	v_mov_b32_e32 v131, v152
	v_xor_b32_e32 v144, 0x80000000, v45
	v_pk_mul_f32 v[130:131], v[130:131], v[130:131]
	v_add_f32_e32 v45, v150, v151
	v_add_f32_e32 v45, v131, v45
	v_add_f32_e32 v45, v130, v45
	v_xor_b32_e32 v42, 0x80000000, v42
	s_mov_b32 s5, 1.0
	v_add_f32_dpp v45, v45, v45 quad_perm:[1,0,3,2] row_mask:0xf bank_mask:0xf bound_ctrl:1
	v_and_b32_e32 v127, 0xffff0000, v72
	v_lshlrev_b32_e32 v56, 16, v72
	v_add_f32_dpp v45, v45, v45 quad_perm:[2,3,0,1] row_mask:0xf bank_mask:0xf bound_ctrl:1
	v_mov_b32_e32 v57, v127
	v_exp_f32_e32 v125, v46
	v_add_f32_dpp v45, v45, v45 row_half_mirror row_mask:0xf bank_mask:0xf bound_ctrl:1
	v_and_b32_e32 v126, s0, v72
	v_and_b32_e32 v141, 0xffff0000, v73
	v_add_f32_dpp v45, v45, v45 row_mirror row_mask:0xf bank_mask:0xf bound_ctrl:1
	v_max_f32_e32 v45, 0x179abe15, v45
	v_rsq_f32_e32 v162, v45
	v_xor_b32_e32 v44, 0x80000000, v44
	v_mov_b32_e32 v45, v132
	v_lshlrev_b32_e32 v138, 16, v73
	v_pk_mul_f32 v[148:149], v[148:149], v[162:163] op_sel_hi:[1,0]
	v_pk_mul_f32 v[136:137], v[136:137], v[162:163]
	v_mov_b32_e32 v134, v148
	v_pk_mul_f32 v[150:151], v[134:135], v[42:43]
	v_pk_mul_f32 v[134:135], v[152:153], v[162:163]
	v_pk_fma_f32 v[42:43], v[4:5], v[132:133], s[4:5]
	v_mov_b32_e32 v46, v149
	v_mov_b32_e32 v135, v43
	v_pk_fma_f32 v[42:43], v[78:79], v[142:143], s[4:5]
	v_pk_mul_f32 v[130:131], v[46:47], v[48:49]
	v_mov_b32_e32 v137, v43
	v_pk_mul_f32 v[42:43], v[150:151], v[56:57] op_sel_hi:[1,0]
	v_mov_b32_e32 v139, v141
	v_pk_mul_f32 v[48:49], v[134:135], v[44:45]
	v_mov_b32_e32 v145, v142
	v_pk_fma_f32 v[44:45], v[150:151], v[56:57], 0 op_sel_hi:[1,0,0]
	v_fma_f32 v46, v10, v43, 0
	v_pk_mul_f32 v[42:43], v[130:131], v[126:127]
	v_mov_b32_e32 v140, v126
	v_pk_mul_f32 v[132:133], v[136:137], v[144:145]
	v_pk_fma_f32 v[44:45], v[130:131], v[56:57], v[44:45] op_sel:[0,1,0]
	v_fmac_f32_e32 v46, v11, v43
	v_pk_mul_f32 v[42:43], v[48:49], v[138:139] op_sel_hi:[1,0]
	v_pk_fma_f32 v[44:45], v[48:49], v[138:139], v[44:45] op_sel_hi:[1,0,1]
	v_fmac_f32_e32 v46, v12, v43
	v_pk_mul_f32 v[42:43], v[132:133], v[140:141]
	v_pk_fma_f32 v[44:45], v[132:133], v[138:139], v[44:45] op_sel:[0,1,0]
	v_fmac_f32_e32 v46, v13, v43
	v_pk_mul_f32 v[128:129], v[122:123], v[56:57]
	v_add_f32_dpp v42, v44, v44 quad_perm:[1,0,3,2] row_mask:0xf bank_mask:0xf bound_ctrl:1
	v_add_f32_dpp v43, v45, v45 quad_perm:[1,0,3,2] row_mask:0xf bank_mask:0xf bound_ctrl:1
	v_add_f32_dpp v46, v46, v46 quad_perm:[1,0,3,2] row_mask:0xf bank_mask:0xf bound_ctrl:1
	v_add_f32_dpp v42, v42, v42 quad_perm:[2,3,0,1] row_mask:0xf bank_mask:0xf bound_ctrl:1
	v_add_f32_dpp v43, v43, v43 quad_perm:[2,3,0,1] row_mask:0xf bank_mask:0xf bound_ctrl:1
	v_lshl_add_u32 v55, v96, 2, s4
	v_pk_mul_f32 v[146:147], v[124:125], v[138:139]
	v_add_f32_dpp v46, v46, v46 quad_perm:[2,3,0,1] row_mask:0xf bank_mask:0xf bound_ctrl:1
	v_add3_u32 v55, v55, v120, v121
	v_mov_b32_e32 v126, v148
	v_mov_b32_e32 v127, v128
	v_mov_b32_e32 v128, v149
	v_add_f32_dpp v42, v42, v42 row_half_mirror row_mask:0xf bank_mask:0xf bound_ctrl:1
	v_add_f32_dpp v43, v43, v43 row_half_mirror row_mask:0xf bank_mask:0xf bound_ctrl:1
	v_add_f32_dpp v46, v46, v46 row_half_mirror row_mask:0xf bank_mask:0xf bound_ctrl:1
	v_mov_b32_e32 v47, v1
	ds_write_b128 v55, v[126:129]
	v_mov_b32_e32 v135, v146
	v_mov_b32_e32 v137, v147
	v_mov_b32_e32 v126, v150
	v_mov_b32_e32 v127, v130
	v_mov_b32_e32 v128, v48
	v_mov_b32_e32 v129, v132
	v_mov_b32_e32 v130, v151
	v_mov_b32_e32 v132, v49
	v_mov_b32_dpp v44, v42 row_mirror row_mask:0xf bank_mask:0xf
	v_mov_b32_dpp v45, v43 row_mirror row_mask:0xf bank_mask:0xf
	v_mov_b32_dpp v47, v46 row_mirror row_mask:0xf bank_mask:0xf
	ds_write_b128 v55, v[134:137] offset:256
	ds_write_b128 v54, v[126:129] offset:24576
	ds_write_b128 v54, v[122:125] offset:16384
	ds_write_b128 v54, v[130:133] offset:32768
	v_lshlrev_b32_e32 v54, 2, v60
	s_and_saveexec_b64 s[18:19], s[44:45]
	s_cbranch_execz .LBB0_842
	v_add_f32_e32 v46, v46, v47
	v_lshl_add_u32 v55, v106, 2, s4
	v_pk_mul_f32 v[48:49], v[52:53], v[46:47] op_sel_hi:[1,0]
	v_pk_mul_f32 v[46:47], v[50:51], v[46:47] op_sel_hi:[1,0]
	v_add_u32_e32 v56, v55, v96
	ds_write_b128 v56, v[46:49] offset:45568
	v_add3_u32 v46, v55, v114, v54
	v_add_u32_e32 v46, 0xa000, v46
	ds_write2_b32 v46, v50, v51 offset1:36
	ds_write2_b32 v46, v52, v53 offset0:72 offset1:108

.LBB0_846:
	s_waitcnt lgkmcnt(1)
	v_mul_f32_e32 v46, 0xbfb8aa3b, v46
	v_exp_f32_e32 v122, v46
	s_waitcnt lgkmcnt(0)
	v_add_f32_e32 v46, -1.0, v42
	v_fma_f32 v135, v6, v46, 1.0
	v_mul_f32_e32 v46, 0xbfb8aa3b, v47
	v_lshlrev_b32_e32 v130, 16, v62
	v_and_b32_e32 v131, 0xffff0000, v62
	v_lshlrev_b32_e32 v132, 16, v63
	v_and_b32_e32 v142, 0xffff0000, v63
	v_exp_f32_e32 v123, v46
	v_add_f32_e32 v46, -1.0, v43
	v_add_f32_e32 v133, -1.0, v44
	v_add_f32_e32 v143, -1.0, v45
	v_fma_f32 v47, v7, v46, 1.0
	v_mul_f32_e32 v46, 0xbfb8aa3b, v48
	v_pk_mul_f32 v[136:137], v[78:79], v[142:143]
	v_pk_mul_f32 v[148:149], v[2:3], v[130:131]
	v_pk_mul_f32 v[152:153], v[4:5], v[132:133]
	v_exp_f32_e32 v124, v46
	v_mul_f32_e32 v46, 0xbfb8aa3b, v49
	v_xor_b32_e32 v48, 0x80000000, v43
	v_mov_b32_e32 v43, v130
	v_pk_mul_f32 v[150:151], v[148:149], v[148:149]
	v_mov_b32_e32 v49, v131
	v_mov_b32_e32 v130, v136
	v_mov_b32_e32 v131, v152
	v_xor_b32_e32 v144, 0x80000000, v45
	v_pk_mul_f32 v[130:131], v[130:131], v[130:131]
	v_add_f32_e32 v45, v150, v151
	v_add_f32_e32 v45, v131, v45
	v_add_f32_e32 v45, v130, v45
	v_xor_b32_e32 v42, 0x80000000, v42
	v_and_b32_e32 v127, 0xffff0000, v64
	v_add_f32_dpp v45, v45, v45 quad_perm:[1,0,3,2] row_mask:0xf bank_mask:0xf bound_ctrl:1
	v_lshlrev_b32_e32 v56, 16, v64
	v_mov_b32_e32 v57, v127
	v_add_f32_dpp v45, v45, v45 quad_perm:[2,3,0,1] row_mask:0xf bank_mask:0xf bound_ctrl:1
	v_exp_f32_e32 v125, v46
	v_and_b32_e32 v126, s0, v64
	v_add_f32_dpp v45, v45, v45 row_half_mirror row_mask:0xf bank_mask:0xf bound_ctrl:1
	v_and_b32_e32 v141, 0xffff0000, v65
	v_xor_b32_e32 v44, 0x80000000, v44
	v_add_f32_dpp v45, v45, v45 row_mirror row_mask:0xf bank_mask:0xf bound_ctrl:1
	v_max_f32_e32 v45, 0x179abe15, v45
	v_rsq_f32_e32 v162, v45
	v_mov_b32_e32 v45, v132
	v_lshlrev_b32_e32 v138, 16, v65
	v_mov_b32_e32 v139, v141
	v_pk_mul_f32 v[148:149], v[148:149], v[162:163] op_sel_hi:[1,0]
	v_pk_mul_f32 v[136:137], v[136:137], v[162:163]
	v_mov_b32_e32 v134, v148
	v_pk_mul_f32 v[150:151], v[134:135], v[42:43]
	v_pk_mul_f32 v[134:135], v[152:153], v[162:163]
	v_pk_fma_f32 v[42:43], v[4:5], v[132:133], s[4:5]
	v_mov_b32_e32 v46, v149
	v_mov_b32_e32 v135, v43
	v_pk_fma_f32 v[42:43], v[78:79], v[142:143], s[4:5]
	v_pk_mul_f32 v[130:131], v[46:47], v[48:49]
	v_mov_b32_e32 v137, v43
	v_pk_mul_f32 v[42:43], v[150:151], v[56:57] op_sel_hi:[1,0]
	v_pk_mul_f32 v[48:49], v[134:135], v[44:45]
	v_mov_b32_e32 v145, v142
	v_pk_fma_f32 v[44:45], v[150:151], v[56:57], 0 op_sel_hi:[1,0,0]
	v_fma_f32 v46, v10, v43, 0
	v_pk_mul_f32 v[42:43], v[130:131], v[126:127]
	v_mov_b32_e32 v140, v126
	v_pk_mul_f32 v[132:133], v[136:137], v[144:145]
	v_pk_fma_f32 v[44:45], v[130:131], v[56:57], v[44:45] op_sel:[0,1,0]
	v_fmac_f32_e32 v46, v11, v43
	v_pk_mul_f32 v[42:43], v[48:49], v[138:139] op_sel_hi:[1,0]
	v_pk_fma_f32 v[44:45], v[48:49], v[138:139], v[44:45] op_sel_hi:[1,0,1]
	v_fmac_f32_e32 v46, v12, v43
	v_pk_mul_f32 v[42:43], v[132:133], v[140:141]
	v_pk_fma_f32 v[44:45], v[132:133], v[138:139], v[44:45] op_sel:[0,1,0]
	v_fmac_f32_e32 v46, v13, v43
	s_nop 1
	v_add_f32_dpp v46, v46, v46 quad_perm:[1,0,3,2] row_mask:0xf bank_mask:0xf bound_ctrl:1
	v_add_f32_dpp v42, v44, v44 quad_perm:[1,0,3,2] row_mask:0xf bank_mask:0xf bound_ctrl:1
	v_add_f32_dpp v43, v45, v45 quad_perm:[1,0,3,2] row_mask:0xf bank_mask:0xf bound_ctrl:1
	v_pk_mul_f32 v[128:129], v[122:123], v[56:57]
	v_add_f32_dpp v42, v42, v42 quad_perm:[2,3,0,1] row_mask:0xf bank_mask:0xf bound_ctrl:1
	v_add_f32_dpp v43, v43, v43 quad_perm:[2,3,0,1] row_mask:0xf bank_mask:0xf bound_ctrl:1
	v_add_f32_dpp v46, v46, v46 quad_perm:[2,3,0,1] row_mask:0xf bank_mask:0xf bound_ctrl:1
	v_lshl_add_u32 v56, v99, 2, s4
	v_pk_mul_f32 v[146:147], v[124:125], v[138:139]
	v_add_f32_dpp v42, v42, v42 row_half_mirror row_mask:0xf bank_mask:0xf bound_ctrl:1
	v_add_f32_dpp v43, v43, v43 row_half_mirror row_mask:0xf bank_mask:0xf bound_ctrl:1
	v_add_f32_dpp v46, v46, v46 row_half_mirror row_mask:0xf bank_mask:0xf bound_ctrl:1
	v_mov_b32_e32 v47, v1
	v_add3_u32 v56, v56, v120, v121
	v_mov_b32_e32 v126, v148
	v_mov_b32_e32 v127, v128
	v_mov_b32_e32 v128, v149
	v_mov_b32_dpp v44, v42 row_mirror row_mask:0xf bank_mask:0xf
	v_mov_b32_dpp v45, v43 row_mirror row_mask:0xf bank_mask:0xf
	v_mov_b32_dpp v47, v46 row_mirror row_mask:0xf bank_mask:0xf
	ds_write_b128 v56, v[126:129]
	v_mov_b32_e32 v135, v146
	v_mov_b32_e32 v137, v147
	v_mov_b32_e32 v126, v150
	v_mov_b32_e32 v127, v130
	v_mov_b32_e32 v128, v48
	v_mov_b32_e32 v129, v132
	v_mov_b32_e32 v130, v151
	v_mov_b32_e32 v132, v49
	ds_write_b128 v56, v[134:137] offset:256
	ds_write_b128 v55, v[126:129] offset:24576
	ds_write_b128 v55, v[122:125] offset:16384
	ds_write_b128 v55, v[130:133] offset:32768
	s_and_saveexec_b64 s[18:19], s[44:45]
	s_cbranch_execz .LBB0_849
	v_add_f32_e32 v46, v46, v47
	v_lshlrev_b32_e32 v55, 2, v106
	v_pk_mul_f32 v[48:49], v[52:53], v[46:47] op_sel_hi:[1,0]
	v_pk_mul_f32 v[46:47], v[50:51], v[46:47] op_sel_hi:[1,0]
	v_add3_u32 v55, s4, v99, v55
	ds_write_b128 v55, v[46:49] offset:45568
	v_add3_u32 v46, s4, v118, v54
	v_add_u32_e32 v46, 0xa000, v46
	ds_write2_b32 v46, v50, v51 offset0:16 offset1:52
	ds_write2_b32 v46, v52, v53 offset0:88 offset1:124
	s_or_b64 exec, exec, s[18:19]
	s_and_saveexec_b64 s[18:19], s[24:25]
	s_cbranch_execnz .LBB0_850
